# radix2: top-16 radix select skipped when <=16 valid blocks; invalid candidates keyed 0 (no per-round mask ANDs); on seldesc+gswap11
# speedup vs baseline: 1.0135x; 1.0056x over previous
.LBB0_1029:
	s_or_b64 exec, exec, s[0:1]
	s_waitcnt lgkmcnt(0)
	s_barrier
	ds_read2st64_b32 v[0:1], v173 offset1:1
	v_add_u32_e32 v7, 0xf0, v174
	ds_read_b64 v[2:3], v161
	ds_read_b64 v[8:9], v162
	ds_read_b64 v[10:11], v163
	ds_read_b64 v[12:13], v164
	ds_read2st64_b32 v[14:15], v174 offset1:1
	ds_read2st64_b32 v[16:17], v174 offset0:33 offset1:34
	ds_read2st64_b32 v[18:19], v174 offset0:66 offset1:67
	ds_read2st64_b32 v[20:21], v174 offset0:99 offset1:100
	ds_read2st64_b32 v[22:23], v7 offset0:30 offset1:31
	ds_read2st64_b32 v[24:25], v7 offset0:63 offset1:64
	ds_read2st64_b32 v[26:27], v7 offset0:96 offset1:97
	ds_read2st64_b32 v[28:29], v7 offset0:129 offset1:130
	ds_read_b64 v[30:31], v165
	ds_read_b64 v[32:33], v166
	ds_read_b64 v[34:35], v167
	ds_read_b64 v[36:37], v168
	ds_read2st64_b32 v[38:39], v7 offset0:162 offset1:163
	ds_read2st64_b32 v[40:41], v7 offset0:195 offset1:196
	ds_read2st64_b32 v[42:43], v7 offset0:228 offset1:229
	ds_read2st64_b32 v[44:45], v174 offset0:132 offset1:133
	ds_read2st64_b32 v[46:47], v174 offset0:165 offset1:166
	ds_read2st64_b32 v[80:81], v174 offset0:198 offset1:199
	ds_read2st64_b32 v[82:83], v174 offset0:231 offset1:232
	s_ashr_i32 s30, s75, 2
	s_add_i32 s31, s30, -1
	s_max_i32 s31, s31, 0
	s_lshl_b32 s98, s40, 25
	s_add_u32 s98, s36, s98
	s_addc_u32 s99, s37, 0
	s_lshl_b32 s20, s29, 7
	s_add_u32 s98, s98, s20
	s_addc_u32 s99, s99, 0
	s_lshl_b32 s20, s47, 20
	s_add_u32 s100, s55, s20
	s_addc_u32 s101, s56, 0
	v_mov_b32_e32 v198, v138
	v_mov_b32_e32 v199, 0
	v_mov_b32_e32 v200, v140
	v_mov_b32_e32 v201, 0
	s_lshl_b32 s22, s30, 18
	s_add_u32 s22, s98, s22
	s_addc_u32 s23, s99, 0
	s_lshl_b32 s24, s30, 7
	s_add_u32 s24, s100, s24
	s_addc_u32 s25, s101, 0
	v_lshl_add_u64 v[194:195], s[22:23], 0, v[198:199]
	v_lshl_add_u64 v[196:197], s[24:25], 0, v[200:201]
	v_lshl_add_u64 v[194:195], v[194:195], 0, v[122:123]
	v_lshl_add_u64 v[196:197], v[196:197], 0, v[122:123]
	global_load_dwordx4 v[240:243], v[194:195], off offset:2560
	global_load_dwordx4 v[244:247], v[196:197], off
	s_lshl_b32 s22, s31, 18
	s_add_u32 s22, s98, s22
	s_addc_u32 s23, s99, 0
	s_lshl_b32 s24, s31, 7
	s_add_u32 s24, s100, s24
	s_addc_u32 s25, s101, 0
	v_lshl_add_u64 v[194:195], s[22:23], 0, v[198:199]
	v_lshl_add_u64 v[196:197], s[24:25], 0, v[200:201]
	v_lshl_add_u64 v[194:195], v[194:195], 0, v[122:123]
	v_lshl_add_u64 v[196:197], v[196:197], 0, v[122:123]
	global_load_dwordx4 v[248:251], v[194:195], off offset:2560
	global_load_dwordx4 v[252:255], v[196:197], off
	s_ashr_i32 s76, s75, 2
	v_cmp_eq_u32_e64 s[0:1], s76, v128
	s_waitcnt lgkmcnt(14)
	v_mov_b32_e32 v84, v1
	v_mov_b32_e32 v85, v0
	v_pk_fma_f32 v[0:1], v[2:3], v[84:85], 0 op_sel_hi:[0,1,0]
	v_mov_b32_e32 v84, v23
	v_mov_b32_e32 v85, v22
	v_pk_fma_f32 v[0:1], v[8:9], v[84:85], v[0:1] op_sel_hi:[0,1,1]
	s_waitcnt lgkmcnt(13)
	v_mov_b32_e32 v22, v25
	v_mov_b32_e32 v23, v24
	v_pk_fma_f32 v[0:1], v[10:11], v[22:23], v[0:1] op_sel_hi:[0,1,1]
	s_waitcnt lgkmcnt(12)
	v_mov_b32_e32 v22, v27
	v_mov_b32_e32 v23, v26
	v_pk_fma_f32 v[0:1], v[12:13], v[22:23], v[0:1] op_sel_hi:[0,1,1]
	s_waitcnt lgkmcnt(11)
	v_mov_b32_e32 v22, v29
	v_mov_b32_e32 v23, v28
	s_waitcnt lgkmcnt(10)
	v_pk_fma_f32 v[0:1], v[30:31], v[22:23], v[0:1] op_sel_hi:[0,1,1]
	s_waitcnt lgkmcnt(6)
	v_mov_b32_e32 v22, v39
	v_mov_b32_e32 v23, v38
	v_pk_fma_f32 v[0:1], v[32:33], v[22:23], v[0:1] op_sel_hi:[0,1,1]
	s_waitcnt lgkmcnt(5)
	v_mov_b32_e32 v22, v41
	v_mov_b32_e32 v23, v40
	v_pk_fma_f32 v[0:1], v[34:35], v[22:23], v[0:1] op_sel_hi:[0,1,1]
	s_waitcnt lgkmcnt(4)
	v_mov_b32_e32 v22, v43
	v_mov_b32_e32 v23, v42
	v_pk_fma_f32 v[0:1], v[36:37], v[22:23], v[0:1] op_sel_hi:[0,1,1]
	v_mov_b32_e32 v22, v15
	v_mov_b32_e32 v23, v14
	v_pk_fma_f32 v[2:3], v[2:3], v[22:23], 0 op_sel:[1,0,0] op_sel_hi:[1,1,0]
	v_mov_b32_e32 v14, v17
	v_mov_b32_e32 v15, v16
	v_pk_fma_f32 v[2:3], v[8:9], v[14:15], v[2:3] op_sel:[1,0,0]
	v_mov_b32_e32 v8, v19
	v_mov_b32_e32 v9, v18
	v_pk_fma_f32 v[2:3], v[10:11], v[8:9], v[2:3] op_sel:[1,0,0]
	v_mov_b32_e32 v8, v21
	v_mov_b32_e32 v9, v20
	v_pk_fma_f32 v[2:3], v[12:13], v[8:9], v[2:3] op_sel:[1,0,0]
	s_waitcnt lgkmcnt(3)
	v_mov_b32_e32 v8, v45
	v_mov_b32_e32 v9, v44
	v_pk_fma_f32 v[2:3], v[30:31], v[8:9], v[2:3] op_sel:[1,0,0]
	s_waitcnt lgkmcnt(2)
	v_mov_b32_e32 v8, v47
	v_mov_b32_e32 v9, v46
	s_add_i32 s24, s76, 0xffffffbf
	s_add_i32 s22, s76, -1
	v_pk_fma_f32 v[2:3], v[32:33], v[8:9], v[2:3] op_sel:[1,0,0]
	s_waitcnt lgkmcnt(1)
	v_mov_b32_e32 v8, v81
	v_mov_b32_e32 v9, v80
	s_or_b64 s[26:27], s[6:7], s[0:1]
	v_cmp_eq_u32_e64 s[0:1], s76, v156
	v_pk_fma_f32 v[2:3], v[34:35], v[8:9], v[2:3] op_sel:[1,0,0]
	s_waitcnt lgkmcnt(0)
	v_mov_b32_e32 v8, v83
	v_mov_b32_e32 v9, v82
	v_cmp_eq_u32_e64 s[22:23], s22, v127
	v_cmp_eq_u32_e64 s[24:25], s24, v128
	v_pk_fma_f32 v[8:9], v[36:37], v[8:9], v[2:3] op_sel:[1,0,0]
	s_or_b64 s[22:23], s[26:27], s[22:23]
	s_or_b64 s[0:1], s[0:1], s[24:25]
	v_cmp_ge_i32_e64 s[20:21], s76, v128
	v_cmp_ge_i32_e32 vcc, s76, v156
	v_cndmask_b32_e64 v3, v1, v182, s[22:23]
	v_cndmask_b32_e64 v2, v0, v182, s[0:1]
	v_cndmask_b32_e64 v1, v9, v182, s[22:23]
	v_cndmask_b32_e64 v0, v8, v182, s[0:1]
	s_mov_b32 s77, 30
	s_mov_b32 s31, 0
	s_mov_b32 s30, 0
	s_mov_b32 s98, 64
	s_mov_b32 s100, 64
	s_cmp_lt_i32 s76, 16
	s_cbranch_scc1 .Lradix_done
	v_cndmask_b32_e64 v8, 0, v3, s[20:21]
	v_cndmask_b32_e32 v9, 0, v2, vcc
	v_cndmask_b32_e64 v10, 0, v1, s[20:21]
	v_cndmask_b32_e32 v11, 0, v0, vcc
.LBB0_1030:
	s_lshl_b32 s0, 1, s77
	s_or_b32 s78, s0, s31
	s_or_b32 s79, s0, s30
	v_cmp_le_u32_e64 s[0:1], s78, v8
	v_cmp_le_u32_e64 s[22:23], s78, v9
	v_cmp_le_u32_e64 s[24:25], s79, v10
	v_cmp_le_u32_e64 s[26:27], s79, v11
	s_bcnt1_i32_b64 s0, s[0:1]
	s_bcnt1_i32_b64 s1, s[22:23]
	s_bcnt1_i32_b64 s22, s[24:25]
	s_bcnt1_i32_b64 s23, s[26:27]
	s_add_i32 s1, s1, s0
	s_add_i32 s23, s23, s22
	s_cmp_gt_u32 s1, 15
	s_cselect_b32 s31, s78, s31
	s_cselect_b32 s98, s1, s98
	s_cmp_gt_u32 s23, 15
	s_cselect_b32 s30, s79, s30
	s_cselect_b32 s100, s23, s100
	s_add_i32 s0, s98, s100
	s_cmp_eq_u32 s0, 32
	s_cbranch_scc1 .Lradix_done
	s_add_i32 s77, s77, -1
	s_cmp_eq_u32 s77, -1
	s_cbranch_scc0 .LBB0_1030
